# P8 GEMM: per-iteration L2 touch of the A panel two iterations ahead of the LDS-DMA
# baseline (speedup 1.0000x reference)
.LBB0_732:
	s_cmp_lt_i32 s50, 9
	s_cselect_b64 s[0:1], -1, 0
	s_and_b64 s[0:1], s[0:1], s[2:3]
	s_andn2_b64 vcc, exec, s[0:1]
	s_cbranch_vccnz .LBB0_757
	s_and_b32 s0, s70, 0xffffffc0
	v_mbcnt_lo_u32_b32 v8, -1, 0
	v_mbcnt_hi_u32_b32 v8, -1, v8
	s_cmpk_gt_i32 s92, 0x3ff
	v_add_u32_e32 v0, s0, v8
	v_and_b32_e32 v246, 0xff, v0
	v_lshlrev_b32_e32 v246, 11, v246
	v_lshrrev_b32_e32 v247, 8, v0
	v_lshl_or_b32 v246, v247, 7, v246
	s_nop 0
	v_readfirstlane_b32 s6, v0
	s_cbranch_scc1 .LBB0_757
	s_ashr_i32 s24, s92, 31
	s_lshr_b32 s0, s24, 29
	s_add_i32 s4, s92, s0
	s_and_b32 s0, s4, -8
	s_sub_i32 s3, s92, s0
	s_cmp_gt_i32 s3, -1
	s_cbranch_scc0 .LBB0_736
	s_lshl_b32 s2, s3, 7
	s_ashr_i32 s0, s4, 3
	s_cbranch_execz .LBB0_737
	s_branch .LBB0_738

.LBB0_750:
	ds_read_b128 v[128:131], v171
	ds_read_b128 v[132:135], v171 offset:1024
	ds_read_b128 v[136:139], v171 offset:2048
	ds_read_b128 v[140:143], v171 offset:3072
	ds_read_b128 v[160:163], v172
	ds_read_b128 v[164:167], v172 offset:1024
	ds_read_b128 v[176:179], v172 offset:2048
	ds_read_b128 v[180:183], v172 offset:3072
	s_add_u32 s98, s18, 0xfffbff80
	s_addc_u32 s99, s19, -1
	global_load_dword v247, v246, s[98:99] offset:512
	s_add_u32 s20, s18, 0xfffc0080
	s_addc_u32 s21, s19, -1
	s_cmp_eq_u32 s46, 12
	s_cselect_b32 s23, s11, s21
	s_cselect_b32 s22, s42, s20
	s_cselect_b32 s21, s9, s45
	s_cselect_b32 s20, s43, s44
	s_add_i32 s47, s40, s25
	v_lshl_add_u64 v[216:217], s[18:19], 0, v[152:153]
	s_mov_b32 m0, s47
	ds_read_b128 v[184:187], v173 offset:16384
	ds_read_b128 v[188:191], v173 offset:17408
	ds_read_b128 v[192:195], v173 offset:18432
	ds_read_b128 v[196:199], v173 offset:19456
	ds_read_b128 v[200:203], v173 offset:20480
	ds_read_b128 v[204:207], v173 offset:21504
	ds_read_b128 v[208:211], v173 offset:22528
	ds_read_b128 v[212:215], v173 offset:23552
	global_load_lds_dwordx4 v[216:217], off
	v_lshl_add_u64 v[216:217], s[18:19], 0, v[154:155]
	s_add_i32 m0, s47, 0x2000
	s_nop 0
	global_load_lds_dwordx4 v[216:217], off
	s_waitcnt vmcnt(8)
	s_waitcnt lgkmcnt(0)
	s_barrier
	s_setprio 1
	s_waitcnt lgkmcnt(0)
	v_mfma_f32_16x16x32_bf16 v[124:127], v[128:131], v[184:187], v[124:127]
	v_mfma_f32_16x16x32_bf16 v[120:123], v[136:139], v[184:187], v[120:123]
	v_mfma_f32_16x16x32_bf16 v[112:115], v[128:131], v[192:195], v[112:115]
	v_mfma_f32_16x16x32_bf16 v[104:107], v[136:139], v[192:195], v[104:107]
	v_mfma_f32_16x16x32_bf16 v[96:99], v[128:131], v[200:203], v[96:99]
	v_mfma_f32_16x16x32_bf16 v[88:91], v[136:139], v[200:203], v[88:91]
	v_mfma_f32_16x16x32_bf16 v[80:83], v[128:131], v[208:211], v[80:83]
	v_mfma_f32_16x16x32_bf16 v[72:75], v[136:139], v[208:211], v[72:75]
	v_mfma_f32_16x16x32_bf16 v[124:127], v[132:135], v[188:191], v[124:127]
	v_mfma_f32_16x16x32_bf16 v[120:123], v[140:143], v[188:191], v[120:123]
	v_mfma_f32_16x16x32_bf16 v[112:115], v[132:135], v[196:199], v[112:115]
	v_mfma_f32_16x16x32_bf16 v[104:107], v[140:143], v[196:199], v[104:107]
	v_mfma_f32_16x16x32_bf16 v[96:99], v[132:135], v[204:207], v[96:99]
	v_mfma_f32_16x16x32_bf16 v[88:91], v[140:143], v[204:207], v[88:91]
	v_mfma_f32_16x16x32_bf16 v[80:83], v[132:135], v[212:215], v[80:83]
	v_mfma_f32_16x16x32_bf16 v[72:75], v[140:143], v[212:215], v[72:75]
	s_setprio 0
	s_setprio 1
	v_mfma_f32_16x16x32_bf16 v[116:119], v[160:163], v[184:187], v[116:119]
	v_mfma_f32_16x16x32_bf16 v[108:111], v[176:179], v[184:187], v[108:111]
	v_mfma_f32_16x16x32_bf16 v[100:103], v[160:163], v[192:195], v[100:103]
	v_mfma_f32_16x16x32_bf16 v[92:95], v[176:179], v[192:195], v[92:95]
	v_mfma_f32_16x16x32_bf16 v[84:87], v[160:163], v[200:203], v[84:87]
	v_mfma_f32_16x16x32_bf16 v[76:79], v[176:179], v[200:203], v[76:79]
	v_mfma_f32_16x16x32_bf16 v[68:71], v[160:163], v[208:211], v[68:71]
	v_mfma_f32_16x16x32_bf16 v[64:67], v[176:179], v[208:211], v[64:67]
	v_mfma_f32_16x16x32_bf16 v[116:119], v[164:167], v[188:191], v[116:119]
	v_mfma_f32_16x16x32_bf16 v[108:111], v[180:183], v[188:191], v[108:111]
	v_mfma_f32_16x16x32_bf16 v[100:103], v[164:167], v[196:199], v[100:103]
	v_mfma_f32_16x16x32_bf16 v[92:95], v[180:183], v[196:199], v[92:95]
	v_mfma_f32_16x16x32_bf16 v[84:87], v[164:167], v[204:207], v[84:87]
	v_mfma_f32_16x16x32_bf16 v[76:79], v[180:183], v[204:207], v[76:79]
	v_mfma_f32_16x16x32_bf16 v[68:71], v[164:167], v[212:215], v[68:71]
	v_mfma_f32_16x16x32_bf16 v[64:67], v[180:183], v[212:215], v[64:67]
	s_setprio 0
	s_barrier
	s_add_i32 s47, s38, s25
	v_lshl_add_u64 v[216:217], s[20:21], 0, v[146:147]
	s_mov_b32 m0, s47
	ds_read_b128 v[184:187], v173 offset:32768
	ds_read_b128 v[188:191], v173 offset:33792
	ds_read_b128 v[192:195], v173 offset:34816
	ds_read_b128 v[196:199], v173 offset:35840
	ds_read_b128 v[200:203], v173 offset:36864
	ds_read_b128 v[204:207], v173 offset:37888
	ds_read_b128 v[208:211], v173 offset:38912
	ds_read_b128 v[212:215], v173 offset:39936
	global_load_lds_dwordx4 v[216:217], off
	s_add_i32 m0, s47, 0x2000
	s_add_u32 s48, s20, 0x40000
	v_lshl_add_u64 v[218:219], s[20:21], 0, v[150:151]
	s_addc_u32 s49, s21, 0
	s_add_i32 s47, s39, s25
	global_load_lds_dwordx4 v[218:219], off
	v_lshl_add_u64 v[220:221], s[48:49], 0, v[146:147]
	s_mov_b32 m0, s47
	v_lshl_add_u64 v[222:223], s[22:23], 0, v[148:149]
	global_load_lds_dwordx4 v[220:221], off
	v_lshl_add_u64 v[220:221], s[48:49], 0, v[150:151]
	s_add_i32 m0, s47, 0x2000
	s_nop 0
	global_load_lds_dwordx4 v[220:221], off
	v_lshl_add_u64 v[220:221], s[22:23], 0, v[144:145]
	s_mov_b32 m0, s17
	s_nop 0
	global_load_lds_dwordx4 v[220:221], off
	s_mov_b32 m0, s26
	s_nop 0
	global_load_lds_dwordx4 v[222:223], off
	s_waitcnt vmcnt(8)
	s_waitcnt lgkmcnt(0)
	s_barrier
	s_setprio 1
	s_waitcnt lgkmcnt(0)
	v_mfma_f32_16x16x32_bf16 v[60:63], v[128:131], v[184:187], v[60:63]
	v_mfma_f32_16x16x32_bf16 v[56:59], v[136:139], v[184:187], v[56:59]
	v_mfma_f32_16x16x32_bf16 v[48:51], v[128:131], v[192:195], v[48:51]
	v_mfma_f32_16x16x32_bf16 v[40:43], v[136:139], v[192:195], v[40:43]
	v_mfma_f32_16x16x32_bf16 v[32:35], v[128:131], v[200:203], v[32:35]
	v_mfma_f32_16x16x32_bf16 v[24:27], v[136:139], v[200:203], v[24:27]
	v_mfma_f32_16x16x32_bf16 v[16:19], v[128:131], v[208:211], v[16:19]
	v_mfma_f32_16x16x32_bf16 v[8:11], v[136:139], v[208:211], v[8:11]
	v_mfma_f32_16x16x32_bf16 v[60:63], v[132:135], v[188:191], v[60:63]
	v_mfma_f32_16x16x32_bf16 v[56:59], v[140:143], v[188:191], v[56:59]
	v_mfma_f32_16x16x32_bf16 v[48:51], v[132:135], v[196:199], v[48:51]
	v_mfma_f32_16x16x32_bf16 v[40:43], v[140:143], v[196:199], v[40:43]
	v_mfma_f32_16x16x32_bf16 v[32:35], v[132:135], v[204:207], v[32:35]
	v_mfma_f32_16x16x32_bf16 v[24:27], v[140:143], v[204:207], v[24:27]
	v_mfma_f32_16x16x32_bf16 v[16:19], v[132:135], v[212:215], v[16:19]
	v_mfma_f32_16x16x32_bf16 v[8:11], v[140:143], v[212:215], v[8:11]
	s_setprio 0
	s_setprio 1
	v_mfma_f32_16x16x32_bf16 v[52:55], v[160:163], v[184:187], v[52:55]
	v_mfma_f32_16x16x32_bf16 v[44:47], v[176:179], v[184:187], v[44:47]
	v_mfma_f32_16x16x32_bf16 v[36:39], v[160:163], v[192:195], v[36:39]
	v_mfma_f32_16x16x32_bf16 v[28:31], v[176:179], v[192:195], v[28:31]
	v_mfma_f32_16x16x32_bf16 v[20:23], v[160:163], v[200:203], v[20:23]
	v_mfma_f32_16x16x32_bf16 v[12:15], v[176:179], v[200:203], v[12:15]
	v_mfma_f32_16x16x32_bf16 v[4:7], v[160:163], v[208:211], v[4:7]
	v_mfma_f32_16x16x32_bf16 v[0:3], v[176:179], v[208:211], v[0:3]
	v_mfma_f32_16x16x32_bf16 v[52:55], v[164:167], v[188:191], v[52:55]
	v_mfma_f32_16x16x32_bf16 v[44:47], v[180:183], v[188:191], v[44:47]
	v_mfma_f32_16x16x32_bf16 v[36:39], v[164:167], v[196:199], v[36:39]
	v_mfma_f32_16x16x32_bf16 v[28:31], v[180:183], v[196:199], v[28:31]
	v_mfma_f32_16x16x32_bf16 v[20:23], v[164:167], v[204:207], v[20:23]
	v_mfma_f32_16x16x32_bf16 v[12:15], v[180:183], v[204:207], v[12:15]
	v_mfma_f32_16x16x32_bf16 v[4:7], v[164:167], v[212:215], v[4:7]
	v_mfma_f32_16x16x32_bf16 v[0:3], v[180:183], v[212:215], v[0:3]
	s_setprio 0
	s_barrier
	s_add_i32 s47, 0, 0x1c000
	s_add_i32 s48, 0, 0x20000
	v_add_u32_e32 v140, s47, v169
	v_add_u32_e32 v175, s48, v169
	ds_read_b128 v[128:131], v140
	ds_read_b128 v[132:135], v140 offset:1024
	ds_read_b128 v[136:139], v140 offset:2048
	ds_read_b128 v[140:143], v140 offset:3072
	ds_read_b128 v[160:163], v175
	ds_read_b128 v[164:167], v175 offset:1024
	ds_read_b128 v[176:179], v175 offset:2048
	ds_read_b128 v[180:183], v175 offset:3072
	s_add_u32 s22, s22, 0x40000
	s_addc_u32 s23, s23, 0
	s_mov_b32 m0, s27
	v_lshl_add_u64 v[224:225], s[22:23], 0, v[144:145]
	ds_read_b128 v[184:187], v173 offset:49152
	ds_read_b128 v[188:191], v173 offset:50176
	ds_read_b128 v[192:195], v173 offset:51200
	ds_read_b128 v[196:199], v173 offset:52224
	ds_read_b128 v[200:203], v173 offset:53248
	ds_read_b128 v[204:207], v173 offset:54272
	ds_read_b128 v[208:211], v173 offset:55296
	ds_read_b128 v[212:215], v173 offset:56320
	global_load_lds_dwordx4 v[224:225], off
	v_lshl_add_u64 v[224:225], s[22:23], 0, v[148:149]
	s_mov_b32 m0, s28
	s_nop 0
	global_load_lds_dwordx4 v[224:225], off
	s_waitcnt vmcnt(8)
	s_waitcnt lgkmcnt(0)
	s_barrier
	s_setprio 1
	s_waitcnt lgkmcnt(0)
	v_mfma_f32_16x16x32_bf16 v[124:127], v[128:131], v[184:187], v[124:127]
	v_mfma_f32_16x16x32_bf16 v[120:123], v[136:139], v[184:187], v[120:123]
	v_mfma_f32_16x16x32_bf16 v[112:115], v[128:131], v[192:195], v[112:115]
	v_mfma_f32_16x16x32_bf16 v[104:107], v[136:139], v[192:195], v[104:107]
	v_mfma_f32_16x16x32_bf16 v[96:99], v[128:131], v[200:203], v[96:99]
	v_mfma_f32_16x16x32_bf16 v[88:91], v[136:139], v[200:203], v[88:91]
	v_mfma_f32_16x16x32_bf16 v[80:83], v[128:131], v[208:211], v[80:83]
	v_mfma_f32_16x16x32_bf16 v[72:75], v[136:139], v[208:211], v[72:75]
	v_mfma_f32_16x16x32_bf16 v[124:127], v[132:135], v[188:191], v[124:127]
	v_mfma_f32_16x16x32_bf16 v[120:123], v[140:143], v[188:191], v[120:123]
	v_mfma_f32_16x16x32_bf16 v[112:115], v[132:135], v[196:199], v[112:115]
	v_mfma_f32_16x16x32_bf16 v[104:107], v[140:143], v[196:199], v[104:107]
	v_mfma_f32_16x16x32_bf16 v[96:99], v[132:135], v[204:207], v[96:99]
	v_mfma_f32_16x16x32_bf16 v[88:91], v[140:143], v[204:207], v[88:91]
	v_mfma_f32_16x16x32_bf16 v[80:83], v[132:135], v[212:215], v[80:83]
	v_mfma_f32_16x16x32_bf16 v[72:75], v[140:143], v[212:215], v[72:75]
	s_setprio 0
	s_setprio 1
	v_mfma_f32_16x16x32_bf16 v[116:119], v[160:163], v[184:187], v[116:119]
	v_mfma_f32_16x16x32_bf16 v[108:111], v[176:179], v[184:187], v[108:111]
	v_mfma_f32_16x16x32_bf16 v[100:103], v[160:163], v[192:195], v[100:103]
	v_mfma_f32_16x16x32_bf16 v[92:95], v[176:179], v[192:195], v[92:95]
	v_mfma_f32_16x16x32_bf16 v[84:87], v[160:163], v[200:203], v[84:87]
	v_mfma_f32_16x16x32_bf16 v[76:79], v[176:179], v[200:203], v[76:79]
	v_mfma_f32_16x16x32_bf16 v[68:71], v[160:163], v[208:211], v[68:71]
	v_mfma_f32_16x16x32_bf16 v[64:67], v[176:179], v[208:211], v[64:67]
	v_mfma_f32_16x16x32_bf16 v[116:119], v[164:167], v[188:191], v[116:119]
	v_mfma_f32_16x16x32_bf16 v[108:111], v[180:183], v[188:191], v[108:111]
	v_mfma_f32_16x16x32_bf16 v[100:103], v[164:167], v[196:199], v[100:103]
	v_mfma_f32_16x16x32_bf16 v[92:95], v[180:183], v[196:199], v[92:95]
	v_mfma_f32_16x16x32_bf16 v[84:87], v[164:167], v[204:207], v[84:87]
	v_mfma_f32_16x16x32_bf16 v[76:79], v[180:183], v[204:207], v[76:79]
	v_mfma_f32_16x16x32_bf16 v[68:71], v[164:167], v[212:215], v[68:71]
	v_mfma_f32_16x16x32_bf16 v[64:67], v[180:183], v[212:215], v[64:67]
	s_setprio 0
	s_barrier
	s_add_i32 s22, s47, s25
	v_lshl_add_u64 v[216:217], v[216:217], 0, s[2:3]
	s_mov_b32 m0, s22
	ds_read_b128 v[184:187], v174
	ds_read_b128 v[188:191], v174 offset:1024
	ds_read_b128 v[192:195], v174 offset:2048
	ds_read_b128 v[196:199], v174 offset:3072
	ds_read_b128 v[200:203], v174 offset:4096
	ds_read_b128 v[204:207], v174 offset:5120
	ds_read_b128 v[208:211], v174 offset:6144
	ds_read_b128 v[212:215], v174 offset:7168
	global_load_lds_dwordx4 v[216:217], off
	s_add_i32 m0, s22, 0x2000
	s_add_u32 s20, s20, 0x40080
	v_lshl_add_u64 v[216:217], v[218:219], 0, s[2:3]
	s_addc_u32 s21, s21, 0
	s_add_i32 s22, s48, s25
	global_load_lds_dwordx4 v[216:217], off
	v_lshl_add_u64 v[216:217], s[20:21], 0, v[146:147]
	s_mov_b32 m0, s22
	s_nop 0
	global_load_lds_dwordx4 v[216:217], off
	v_lshl_add_u64 v[216:217], s[20:21], 0, v[150:151]
	s_add_i32 m0, s22, 0x2000
	s_nop 0
	global_load_lds_dwordx4 v[216:217], off
	v_lshl_add_u64 v[216:217], v[220:221], 0, s[2:3]
	s_mov_b32 m0, s33
	s_nop 0
	global_load_lds_dwordx4 v[216:217], off
	v_lshl_add_u64 v[216:217], v[222:223], 0, s[2:3]
	s_mov_b32 m0, s34
	s_nop 0
	global_load_lds_dwordx4 v[216:217], off
	s_waitcnt vmcnt(8)
	s_waitcnt lgkmcnt(0)
	s_barrier
	s_setprio 1
	s_waitcnt lgkmcnt(0)
	v_mfma_f32_16x16x32_bf16 v[60:63], v[128:131], v[184:187], v[60:63]
	v_mfma_f32_16x16x32_bf16 v[56:59], v[136:139], v[184:187], v[56:59]
	v_mfma_f32_16x16x32_bf16 v[48:51], v[128:131], v[192:195], v[48:51]
	v_mfma_f32_16x16x32_bf16 v[40:43], v[136:139], v[192:195], v[40:43]
	v_mfma_f32_16x16x32_bf16 v[32:35], v[128:131], v[200:203], v[32:35]
	v_mfma_f32_16x16x32_bf16 v[24:27], v[136:139], v[200:203], v[24:27]
	v_mfma_f32_16x16x32_bf16 v[16:19], v[128:131], v[208:211], v[16:19]
	v_mfma_f32_16x16x32_bf16 v[8:11], v[136:139], v[208:211], v[8:11]
	v_mfma_f32_16x16x32_bf16 v[60:63], v[132:135], v[188:191], v[60:63]
	v_mfma_f32_16x16x32_bf16 v[56:59], v[140:143], v[188:191], v[56:59]
	v_mfma_f32_16x16x32_bf16 v[48:51], v[132:135], v[196:199], v[48:51]
	v_mfma_f32_16x16x32_bf16 v[40:43], v[140:143], v[196:199], v[40:43]
	v_mfma_f32_16x16x32_bf16 v[32:35], v[132:135], v[204:207], v[32:35]
	v_mfma_f32_16x16x32_bf16 v[24:27], v[140:143], v[204:207], v[24:27]
	v_mfma_f32_16x16x32_bf16 v[16:19], v[132:135], v[212:215], v[16:19]
	v_mfma_f32_16x16x32_bf16 v[8:11], v[140:143], v[212:215], v[8:11]
	s_setprio 0
	s_setprio 1
	v_mfma_f32_16x16x32_bf16 v[52:55], v[160:163], v[184:187], v[52:55]
	v_mfma_f32_16x16x32_bf16 v[44:47], v[176:179], v[184:187], v[44:47]
	v_mfma_f32_16x16x32_bf16 v[36:39], v[160:163], v[192:195], v[36:39]
	v_mfma_f32_16x16x32_bf16 v[28:31], v[176:179], v[192:195], v[28:31]
	v_mfma_f32_16x16x32_bf16 v[20:23], v[160:163], v[200:203], v[20:23]
	v_mfma_f32_16x16x32_bf16 v[12:15], v[176:179], v[200:203], v[12:15]
	v_mfma_f32_16x16x32_bf16 v[4:7], v[160:163], v[208:211], v[4:7]
	v_mfma_f32_16x16x32_bf16 v[0:3], v[176:179], v[208:211], v[0:3]
	v_mfma_f32_16x16x32_bf16 v[52:55], v[164:167], v[188:191], v[52:55]
	v_mfma_f32_16x16x32_bf16 v[44:47], v[180:183], v[188:191], v[44:47]
	v_mfma_f32_16x16x32_bf16 v[36:39], v[164:167], v[196:199], v[36:39]
	v_mfma_f32_16x16x32_bf16 v[28:31], v[180:183], v[196:199], v[28:31]
	v_mfma_f32_16x16x32_bf16 v[20:23], v[164:167], v[204:207], v[20:23]
	v_mfma_f32_16x16x32_bf16 v[12:15], v[180:183], v[204:207], v[12:15]
	v_mfma_f32_16x16x32_bf16 v[4:7], v[164:167], v[212:215], v[4:7]
	v_mfma_f32_16x16x32_bf16 v[0:3], v[180:183], v[212:215], v[0:3]
	s_setprio 0
	s_barrier
	s_add_i32 s46, s46, 2
	s_add_u32 s18, s18, 0x100
	s_addc_u32 s19, s19, 0
	s_add_u32 s44, s44, 0x100
	s_addc_u32 s45, s45, 0
	s_cmp_gt_u32 s46, 13
	s_cbranch_scc0 .LBB0_750
	s_and_b64 vcc, exec, s[6:7]
	s_cbranch_vccz .LBB0_753
	s_barrier
